# attention tile loads: drop 64-bit VALU pointer math (SGPR bases + saddr loads) in diff/NSA stream loops
# speedup vs baseline: 1.0350x; 1.0085x over previous
.LBB0_44:
	s_cmpk_gt_i32 s54, 0x7ff
	s_cbranch_scc1 .LBB0_43
	s_waitcnt vmcnt(10)
	v_mov_b32_e32 v54, v224
	s_ashr_i32 s55, s54, 5
	v_readfirstlane_b32 s0, v54
	s_sub_i32 s57, 63, s55
	s_ashr_i32 s0, s0, 1
	s_lshl_b32 s1, s57, 7
	s_and_b32 s52, s0, 0xffffffe0
	s_add_i32 s52, s52, s1
	s_bfe_u32 s56, s54, 0x10004
	s_and_b32 s48, s54, 15
	v_and_or_b32 v170, v54, 15, s52
	s_lshl_b32 s94, s56, 13
	s_lshl_b32 s0, s48, 7
	v_ashrrev_i32_e32 v171, 31, v170
	s_add_u32 s0, s13, s0
	v_lshl_add_u64 v[172:173], v[170:171], 0, s[94:95]
	s_addc_u32 s1, s14, 0
	v_and_b32_e32 v0, 16, v54
	v_lshlrev_b64 v[2:3], 11, v[172:173]
	v_cmp_eq_u32_e64 s[40:41], 0, v0
	s_waitcnt vmcnt(1)
	v_lshl_add_u64 v[14:15], s[0:1], 0, v[2:3]
	v_and_b32_e32 v0, 48, v54
	v_lshl_add_u64 v[6:7], v[14:15], 0, v[0:1]
	v_lshlrev_b64 v[10:11], 6, v[170:171]
	global_load_dwordx4 v[2:5], v[6:7], off offset:64
	s_nop 0
	global_load_dwordx4 v[6:9], v[6:7], off
	v_lshl_add_u64 v[22:23], s[4:5], 0, v[10:11]
	global_load_dwordx4 v[10:13], v[14:15], off
	s_nop 0
	global_load_dwordx4 v[14:17], v[14:15], off offset:16
	v_or_b32_e32 v176, 16, v170
	v_and_b32_e32 v55, 63, v54
	v_ashrrev_i32_e32 v177, 31, v176
	v_cmp_gt_u32_e32 vcc, 32, v55
	v_lshl_add_u64 v[174:175], v[176:177], 0, s[94:95]
	v_mov_b32_e32 v90, v1
	v_mov_b32_e32 v91, v1
	v_mov_b32_e32 v92, v1
	v_mov_b32_e32 v93, v1
	v_lshlrev_b32_e32 v193, 4, v54
	v_lshlrev_b32_e32 v197, 4, v55
	v_mov_b64_e32 v[70:71], v[90:91]
	v_mov_b64_e32 v[104:105], v[92:93]
	v_mov_b64_e32 v[66:67], v[90:91]
	v_mov_b64_e32 v[100:101], v[92:93]
	v_mov_b64_e32 v[58:59], v[90:91]
	v_mov_b64_e32 v[96:97], v[92:93]
	v_mov_b64_e32 v[86:87], v[90:91]
	v_mov_b64_e32 v[82:83], v[90:91]
	v_mov_b64_e32 v[78:79], v[90:91]
	v_mov_b64_e32 v[74:75], v[90:91]
	s_mov_b32 s49, 63
	s_mov_b32 s53, 0
	v_mov_b32_e32 v200, 0xf149f2ca
	v_mov_b32_e32 v198, 0xf149f2ca
	v_mov_b64_e32 v[72:73], v[92:93]
	v_mov_b64_e32 v[102:103], v[90:91]
	v_mov_b64_e32 v[68:69], v[92:93]
	v_mov_b64_e32 v[98:99], v[90:91]
	v_mov_b64_e32 v[60:61], v[92:93]
	v_mov_b64_e32 v[94:95], v[90:91]
	v_mov_b64_e32 v[88:89], v[92:93]
	v_mov_b64_e32 v[84:85], v[92:93]
	v_mov_b64_e32 v[80:81], v[92:93]
	v_mov_b64_e32 v[76:77], v[92:93]
	s_waitcnt vmcnt(1)
	v_lshlrev_b32_e32 v26, 16, v10
	s_waitcnt vmcnt(0)
	v_lshlrev_b32_e32 v27, 16, v14
	v_and_b32_e32 v29, 0xffff0000, v14
	v_and_b32_e32 v28, 0xffff0000, v10
	v_lshlrev_b32_e32 v31, 16, v15
	v_lshlrev_b32_e32 v30, 16, v11
	v_and_b32_e32 v33, 0xffff0000, v15
	v_and_b32_e32 v32, 0xffff0000, v11
	v_lshlrev_b32_e32 v35, 16, v16
	v_lshlrev_b32_e32 v34, 16, v12
	v_and_b32_e32 v37, 0xffff0000, v16
	v_and_b32_e32 v36, 0xffff0000, v12
	v_lshlrev_b32_e32 v39, 16, v17
	v_lshlrev_b32_e32 v38, 16, v13
	v_and_b32_e32 v41, 0xffff0000, v17
	v_and_b32_e32 v40, 0xffff0000, v13
	global_load_dwordx4 v[10:13], v[22:23], off offset:48
	global_load_dwordx4 v[14:17], v[22:23], off offset:16
	global_load_dwordx4 v[18:21], v[22:23], off offset:32
	s_nop 0
	global_load_dwordx4 v[22:25], v[22:23], off
	s_waitcnt vmcnt(1)
	v_mov_b32_e32 v43, v18
	s_waitcnt vmcnt(0)
	v_mov_b32_e32 v42, v22
	v_pk_mul_f32 v[42:43], v[42:43], v[26:27]
	s_nop 0
	v_sub_f32_e32 v44, v42, v43
	v_mov_b32_e32 v42, v18
	v_mov_b32_e32 v43, v22
	v_pk_mul_f32 v[26:27], v[42:43], v[26:27]
	v_mov_b32_e32 v22, v19
	v_add_f32_e32 v18, v26, v27
	v_cndmask_b32_e64 v42, v18, v44, s[40:41]
	v_mov_b32_e32 v18, v23
	v_pk_mul_f32 v[26:27], v[18:19], v[28:29]
	v_pk_mul_f32 v[18:19], v[22:23], v[28:29]
	v_sub_f32_e32 v26, v26, v27
	v_add_f32_e32 v18, v19, v18
	v_cndmask_b32_e64 v22, v18, v26, s[40:41]
	v_mov_b32_e32 v18, v24
	v_mov_b32_e32 v19, v20
	v_pk_mul_f32 v[18:19], v[18:19], v[30:31]
	s_nop 0
	v_sub_f32_e32 v23, v18, v19
	v_mov_b32_e32 v18, v20
	v_mov_b32_e32 v19, v24
	v_pk_mul_f32 v[18:19], v[18:19], v[30:31]
	v_mov_b32_e32 v20, v25
	v_add_f32_e32 v18, v19, v18
	v_cndmask_b32_e64 v23, v18, v23, s[40:41]
	v_pk_mul_f32 v[18:19], v[20:21], v[32:33]
	v_mov_b32_e32 v24, v21
	v_sub_f32_e32 v20, v18, v19
	v_pk_mul_f32 v[18:19], v[24:25], v[32:33]
	s_nop 0
	v_add_f32_e32 v18, v19, v18
	v_cndmask_b32_e64 v20, v18, v20, s[40:41]
	v_mov_b32_e32 v18, v14
	v_mov_b32_e32 v19, v10
	v_pk_mul_f32 v[18:19], v[18:19], v[34:35]
	s_nop 0
	v_sub_f32_e32 v21, v18, v19
	v_mov_b32_e32 v18, v10
	v_mov_b32_e32 v19, v14
	v_pk_mul_f32 v[18:19], v[18:19], v[34:35]
	v_mov_b32_e32 v14, v11
	v_add_f32_e32 v10, v19, v18
	v_cndmask_b32_e64 v21, v10, v21, s[40:41]
	v_mov_b32_e32 v10, v15
	v_pk_mul_f32 v[18:19], v[10:11], v[36:37]
	v_pk_mul_f32 v[10:11], v[14:15], v[36:37]
	v_sub_f32_e32 v18, v18, v19
	v_add_f32_e32 v10, v11, v10
	v_cndmask_b32_e64 v14, v10, v18, s[40:41]
	v_mov_b32_e32 v10, v16
	v_mov_b32_e32 v11, v12
	v_pk_mul_f32 v[10:11], v[10:11], v[38:39]
	v_lshlrev_b64 v[18:19], 6, v[176:177]
	v_sub_f32_e32 v15, v10, v11
	v_mov_b32_e32 v10, v12
	v_mov_b32_e32 v11, v16
	v_pk_mul_f32 v[10:11], v[10:11], v[38:39]
	v_mov_b32_e32 v12, v17
	v_add_f32_e32 v10, v11, v10
	v_cndmask_b32_e64 v15, v10, v15, s[40:41]
	v_pk_mul_f32 v[10:11], v[12:13], v[40:41]
	v_mov_b32_e32 v16, v13
	v_sub_f32_e32 v12, v10, v11
	v_pk_mul_f32 v[10:11], v[16:17], v[40:41]
	v_cvt_pk_bf16_f32 v13, v21, v14
	v_add_f32_e32 v10, v11, v10
	v_cndmask_b32_e64 v10, v10, v12, s[40:41]
	v_cvt_pk_bf16_f32 v11, v42, v22
	v_cvt_pk_bf16_f32 v10, v15, v10
	v_cndmask_b32_e32 v9, v9, v10, vcc
	v_cndmask_b32_e32 v6, v6, v11, vcc
	v_lshlrev_b64 v[10:11], 11, v[174:175]
	v_cvt_pk_bf16_f32 v12, v23, v20
	v_lshl_add_u64 v[22:23], s[0:1], 0, v[10:11]
	v_lshl_add_u64 v[14:15], v[22:23], 0, v[0:1]
	v_cndmask_b32_e32 v8, v8, v13, vcc
	v_cndmask_b32_e32 v7, v7, v12, vcc
	global_load_dwordx4 v[10:13], v[14:15], off offset:64
	s_nop 0
	global_load_dwordx4 v[14:17], v[14:15], off
	v_lshl_add_u64 v[30:31], s[4:5], 0, v[18:19]
	global_load_dwordx4 v[18:21], v[22:23], off
	s_nop 0
	global_load_dwordx4 v[22:25], v[22:23], off offset:16
	s_waitcnt vmcnt(1)
	v_lshlrev_b32_e32 v48, 16, v18
	s_waitcnt vmcnt(0)
	v_lshlrev_b32_e32 v49, 16, v22
	v_and_b32_e32 v47, 0xffff0000, v22
	v_and_b32_e32 v46, 0xffff0000, v18
	v_lshlrev_b32_e32 v45, 16, v23
	v_lshlrev_b32_e32 v44, 16, v19
	v_and_b32_e32 v43, 0xffff0000, v23
	v_and_b32_e32 v42, 0xffff0000, v19
	v_lshlrev_b32_e32 v41, 16, v24
	v_lshlrev_b32_e32 v40, 16, v20
	v_and_b32_e32 v39, 0xffff0000, v24
	v_and_b32_e32 v38, 0xffff0000, v20
	v_lshlrev_b32_e32 v37, 16, v25
	v_lshlrev_b32_e32 v36, 16, v21
	v_and_b32_e32 v35, 0xffff0000, v25
	v_and_b32_e32 v34, 0xffff0000, v21
	global_load_dwordx4 v[18:21], v[30:31], off offset:48
	global_load_dwordx4 v[22:25], v[30:31], off offset:16
	global_load_dwordx4 v[26:29], v[30:31], off offset:32
	s_nop 0
	global_load_dwordx4 v[30:33], v[30:31], off
	s_barrier
	s_waitcnt vmcnt(1)
	v_mov_b32_e32 v51, v26
	s_waitcnt vmcnt(0)
	v_mov_b32_e32 v50, v30
	v_pk_mul_f32 v[50:51], v[50:51], v[48:49]
	s_nop 0
	v_sub_f32_e32 v0, v50, v51
	v_mov_b32_e32 v50, v26
	v_mov_b32_e32 v51, v30
	v_pk_mul_f32 v[48:49], v[50:51], v[48:49]
	v_mov_b32_e32 v30, v27
	v_add_f32_e32 v26, v48, v49
	v_cndmask_b32_e64 v0, v26, v0, s[40:41]
	v_mov_b32_e32 v26, v31
	v_pk_mul_f32 v[48:49], v[26:27], v[46:47]
	v_pk_mul_f32 v[26:27], v[30:31], v[46:47]
	v_sub_f32_e32 v48, v48, v49
	v_add_f32_e32 v26, v27, v26
	v_cndmask_b32_e64 v30, v26, v48, s[40:41]
	v_mov_b32_e32 v26, v32
	v_mov_b32_e32 v27, v28
	v_pk_mul_f32 v[26:27], v[26:27], v[44:45]
	v_cvt_pk_bf16_f32 v0, v0, v30
	v_sub_f32_e32 v31, v26, v27
	v_mov_b32_e32 v26, v28
	v_mov_b32_e32 v27, v32
	v_pk_mul_f32 v[26:27], v[26:27], v[44:45]
	v_mov_b32_e32 v28, v33
	v_add_f32_e32 v26, v27, v26
	v_cndmask_b32_e64 v31, v26, v31, s[40:41]
	v_pk_mul_f32 v[26:27], v[28:29], v[42:43]
	v_mov_b32_e32 v32, v29
	v_sub_f32_e32 v28, v26, v27
	v_pk_mul_f32 v[26:27], v[32:33], v[42:43]
	v_cndmask_b32_e32 v14, v14, v0, vcc
	v_add_f32_e32 v26, v27, v26
	v_cndmask_b32_e64 v28, v26, v28, s[40:41]
	v_mov_b32_e32 v26, v22
	v_mov_b32_e32 v27, v18
	v_pk_mul_f32 v[26:27], v[26:27], v[40:41]
	v_mov_b64_e32 v[46:47], v[90:91]
	v_sub_f32_e32 v29, v26, v27
	v_mov_b32_e32 v26, v18
	v_mov_b32_e32 v27, v22
	v_pk_mul_f32 v[26:27], v[26:27], v[40:41]
	v_mov_b32_e32 v22, v19
	v_add_f32_e32 v18, v27, v26
	v_cndmask_b32_e64 v29, v18, v29, s[40:41]
	v_mov_b32_e32 v18, v23
	v_pk_mul_f32 v[26:27], v[18:19], v[38:39]
	v_pk_mul_f32 v[18:19], v[22:23], v[38:39]
	v_sub_f32_e32 v26, v26, v27
	v_add_f32_e32 v18, v19, v18
	v_cndmask_b32_e64 v22, v18, v26, s[40:41]
	v_mov_b32_e32 v18, v24
	v_mov_b32_e32 v19, v20
	v_pk_mul_f32 v[18:19], v[18:19], v[36:37]
	v_lshlrev_b32_e32 v26, 3, v54
	v_sub_f32_e32 v23, v18, v19
	v_mov_b32_e32 v18, v20
	v_mov_b32_e32 v19, v24
	v_pk_mul_f32 v[18:19], v[18:19], v[36:37]
	v_mov_b32_e32 v20, v25
	v_add_f32_e32 v18, v19, v18
	v_cndmask_b32_e64 v23, v18, v23, s[40:41]
	v_pk_mul_f32 v[18:19], v[20:21], v[34:35]
	v_mov_b32_e32 v24, v21
	v_sub_f32_e32 v20, v18, v19
	v_pk_mul_f32 v[18:19], v[24:25], v[34:35]
	v_ashrrev_i32_e32 v27, 31, v26
	v_add_f32_e32 v18, v19, v18
	v_cndmask_b32_e64 v18, v18, v20, s[40:41]
	s_lshl_b32 s40, s54, 20
	v_cvt_pk_bf16_f32 v20, v29, v22
	s_and_b32 s0, s40, 0x1f00000
	v_add_u32_e32 v22, 0x800, v26
	v_cvt_pk_bf16_f32 v18, v23, v18
	s_add_u32 s0, s15, s0
	v_ashrrev_i32_e32 v23, 31, v22
	v_cvt_pk_bf16_f32 v19, v31, v28
	s_addc_u32 s1, s44, 0
	v_lshlrev_b64 v[28:29], 1, v[26:27]
	v_lshlrev_b64 v[34:35], 1, v[22:23]
	v_cndmask_b32_e32 v17, v17, v18, vcc
	v_cndmask_b32_e32 v15, v15, v19, vcc
	v_lshl_add_u64 v[18:19], s[0:1], 0, v[28:29]
	v_lshl_add_u64 v[22:23], s[0:1], 0, v[34:35]
	s_and_b32 s0, s40, 0xe00000
	s_lshl_b32 s1, s56, 24
	s_lshl_b32 s41, s57, 1
	s_or_b32 s40, s1, s0
	s_add_u32 s0, s45, s40
	s_addc_u32 s1, s46, 0
	v_lshl_add_u64 v[30:31], s[0:1], 0, v[28:29]
	v_lshl_add_u64 v[36:37], s[0:1], 0, v[34:35]
	global_load_dwordx4 v[30:33], v[30:31], off
	v_cndmask_b32_e32 v16, v16, v20, vcc
	global_load_dwordx4 v[42:45], v[36:37], off
	v_add_u32_e32 v36, 0x1000, v26
	v_ashrrev_i32_e32 v37, 31, v36
	v_add_u32_e32 v26, 0x1800, v26
	v_lshlrev_b64 v[36:37], 1, v[36:37]
	v_ashrrev_i32_e32 v27, 31, v26
	v_lshl_add_u64 v[38:39], s[0:1], 0, v[36:37]
	v_lshlrev_b64 v[26:27], 1, v[26:27]
	global_load_dwordx4 v[50:53], v[38:39], off
	v_lshl_add_u64 v[38:39], s[0:1], 0, v[26:27]
	global_load_dwordx4 v[18:21], v[18:19], off
	s_add_i32 s0, s41, 2
	global_load_dwordx4 v[22:25], v[22:23], off
	v_readlane_b32 s1, v254, 13
	global_load_dwordx4 v[62:65], v[38:39], off
	s_add_u32 s40, s1, s40
	v_readlane_b32 s1, v254, 14
	v_cmp_lt_i32_e32 vcc, v247, v214
	s_addc_u32 s41, s1, 0
	s_and_b32 s1, s54, 31
	v_cndmask_b32_e32 v0, v225, v247, vcc
	v_cmp_lt_i32_e32 vcc, v246, v214
	v_mov_b32_e32 v180, v34
	s_mov_b64 s[98:99], s[40:41]
	v_mov_b32_e32 v184, v26
	s_lshl_b32 s1, s1, 20
	v_readlane_b32 s40, v254, 15
	v_lshlrev_b32_e32 v177, 2, v0
	v_cndmask_b32_e32 v0, v225, v246, vcc
	s_add_u32 s40, s40, s1
	v_readlane_b32 s1, v254, 16
	v_lshlrev_b32_e32 v171, 2, v0
	v_lshrrev_b32_e32 v0, 2, v54
	s_addc_u32 s41, s1, 0
	v_and_b32_e32 v192, 12, v0
	s_mov_b64 s[2:3], s[40:41]
	s_lshl_b32 s1, s55, 1
	v_mov_b32_e32 v0, v1
	v_mov_b64_e32 v[54:55], v[90:91]
	v_mov_b64_e32 v[38:39], v[90:91]
	v_mov_b64_e32 v[34:35], v[90:91]
	v_mov_b64_e32 v[26:27], v[90:91]
	s_sub_i32 s1, 0, s1
	s_movk_i32 s54, 0xff80
	v_mov_b64_e32 v[56:57], v[92:93]
	v_mov_b64_e32 v[48:49], v[92:93]
	v_mov_b64_e32 v[40:41], v[92:93]
	v_mov_b64_e32 v[36:37], v[92:93]
	v_mov_b64_e32 v[28:29], v[92:93]
	v_mov_b64_e32 v[178:179], v[0:1]
.LBB0_46:
	s_mul_i32 s40, s53, 0x6000
	s_add_i32 s41, s54, 0x81
	v_add_u32_e32 v0, s40, v193
	s_cmp_ge_u32 s41, s0
	s_waitcnt vmcnt(2)
	ds_write_b128 v0, v[18:21]
	s_waitcnt vmcnt(1)
	ds_write_b128 v0, v[22:25] offset:4096
	ds_write_b128 v0, v[30:33] offset:8192
	ds_write_b128 v0, v[42:45] offset:12288
	ds_write_b128 v0, v[50:53] offset:16384
	s_waitcnt vmcnt(0)
	ds_write_b128 v0, v[62:65] offset:20480
	s_waitcnt lgkmcnt(0)
	s_barrier
	s_cbranch_scc1 .LBB0_48
	global_load_dwordx4 v[18:21], v180, s[2:3] offset:-4096
	global_load_dwordx4 v[22:25], v180, s[2:3]
	global_load_dwordx4 v[30:33], v180, s[98:99] offset:-4096
	global_load_dwordx4 v[42:45], v180, s[98:99]
	global_load_dwordx4 v[50:53], v184, s[98:99] offset:-4096
	global_load_dwordx4 v[62:65], v184, s[98:99]

.LBB0_52:
	v_mul_f32_e32 v195, 0xbe38aa3b, v199
	v_fmamk_f32 v167, v167, 0x3e38aa3b, v195
	v_exp_f32_e32 v194, v167
	v_fmamk_f32 v167, v168, 0x3e38aa3b, v195
	v_fmamk_f32 v163, v163, 0x3e38aa3b, v195
	v_fmamk_f32 v159, v159, 0x3e38aa3b, v195
	v_mul_f32_e32 v196, 0xbe38aa3b, v201
	v_fmamk_f32 v166, v166, 0x3e38aa3b, v195
	v_exp_f32_e32 v168, v167
	v_fmamk_f32 v167, v169, 0x3e38aa3b, v195
	v_exp_f32_e32 v204, v163
	v_fmamk_f32 v163, v164, 0x3e38aa3b, v195
	v_exp_f32_e32 v208, v159
	v_fmamk_f32 v159, v160, 0x3e38aa3b, v195
	v_fmamk_f32 v155, v155, 0x3e38aa3b, v195
	v_fmamk_f32 v150, v150, 0x3e38aa3b, v196
	v_exp_f32_e32 v166, v166
	v_exp_f32_e32 v202, v167
	v_fmamk_f32 v162, v162, 0x3e38aa3b, v195
	v_exp_f32_e32 v164, v163
	v_fmamk_f32 v163, v165, 0x3e38aa3b, v195
	v_fmamk_f32 v158, v158, 0x3e38aa3b, v195
	v_exp_f32_e32 v160, v159
	v_fmamk_f32 v159, v161, 0x3e38aa3b, v195
	v_fmamk_f32 v154, v154, 0x3e38aa3b, v195
	v_exp_f32_e32 v212, v155
	v_fmamk_f32 v155, v156, 0x3e38aa3b, v195
	v_fmac_f32_e32 v195, 0x3e38aa3b, v157
	v_exp_f32_e32 v167, v150
	v_fmamk_f32 v150, v151, 0x3e38aa3b, v196
	v_exp_f32_e32 v216, v195
	v_exp_f32_e32 v195, v150
	v_fmamk_f32 v150, v152, 0x3e38aa3b, v196
	v_exp_f32_e32 v169, v150
	v_fmamk_f32 v150, v153, 0x3e38aa3b, v196
	v_exp_f32_e32 v203, v150
	v_fmamk_f32 v146, v146, 0x3e38aa3b, v196
	v_exp_f32_e32 v162, v162
	v_exp_f32_e32 v206, v163
	v_exp_f32_e32 v163, v146
	v_fmamk_f32 v146, v147, 0x3e38aa3b, v196
	v_pk_add_f32 v[150:151], v[166:167], 0 op_sel_hi:[1,0]
	v_exp_f32_e32 v205, v146
	v_fmamk_f32 v146, v148, 0x3e38aa3b, v196
	v_pk_add_f32 v[150:151], v[194:195], v[150:151]
	v_exp_f32_e32 v165, v146
	v_fmamk_f32 v146, v149, 0x3e38aa3b, v196
	v_pk_add_f32 v[150:151], v[168:169], v[150:151]
	v_exp_f32_e32 v207, v146
	v_pk_add_f32 v[150:151], v[202:203], v[150:151]
	v_fmamk_f32 v142, v142, 0x3e38aa3b, v196
	v_exp_f32_e32 v158, v158
	v_exp_f32_e32 v210, v159
	v_pk_add_f32 v[150:151], v[162:163], v[150:151]
	v_exp_f32_e32 v159, v142
	v_fmamk_f32 v142, v143, 0x3e38aa3b, v196
	v_pk_add_f32 v[150:151], v[204:205], v[150:151]
	v_exp_f32_e32 v209, v142
	v_fmamk_f32 v142, v144, 0x3e38aa3b, v196
	v_fmamk_f32 v138, v138, 0x3e38aa3b, v196
	v_exp_f32_e32 v156, v155
	v_pk_add_f32 v[150:151], v[164:165], v[150:151]
	v_exp_f32_e32 v161, v142
	v_fmamk_f32 v142, v145, 0x3e38aa3b, v196
	v_exp_f32_e32 v155, v138
	v_fmamk_f32 v138, v139, 0x3e38aa3b, v196
	v_pk_add_f32 v[150:151], v[206:207], v[150:151]
	v_exp_f32_e32 v211, v142
	v_exp_f32_e32 v213, v138
	v_fmamk_f32 v138, v140, 0x3e38aa3b, v196
	v_exp_f32_e32 v154, v154
	v_exp_f32_e32 v157, v138
	v_pk_add_f32 v[138:139], v[158:159], v[150:151]
	v_fmac_f32_e32 v196, 0x3e38aa3b, v141
	v_pk_add_f32 v[138:139], v[208:209], v[138:139]
	v_exp_f32_e32 v217, v196
	v_pk_add_f32 v[138:139], v[160:161], v[138:139]
	v_cvt_pk_bf16_f32 v146, v166, v194
	v_pk_add_f32 v[138:139], v[210:211], v[138:139]
	v_cvt_pk_bf16_f32 v147, v168, v202
	v_pk_add_f32 v[138:139], v[154:155], v[138:139]
	v_cvt_pk_bf16_f32 v148, v162, v204
	v_pk_add_f32 v[138:139], v[212:213], v[138:139]
	v_cvt_pk_bf16_f32 v149, v164, v206
	v_pk_add_f32 v[138:139], v[156:157], v[138:139]
	v_cvt_pk_bf16_f32 v140, v154, v212
	v_pk_add_f32 v[142:143], v[216:217], v[138:139]
	v_cvt_pk_bf16_f32 v138, v158, v208
	v_cvt_pk_bf16_f32 v139, v160, v210
	v_cvt_pk_bf16_f32 v141, v156, v216
	v_pk_add_f32 v[178:179], v[142:143], v[178:179]
	v_cvt_pk_bf16_f32 v142, v167, v195
	v_cvt_pk_bf16_f32 v143, v169, v203
	v_cvt_pk_bf16_f32 v144, v163, v205
	v_cvt_pk_bf16_f32 v145, v165, v207
	v_cvt_pk_bf16_f32 v150, v159, v209
	v_cvt_pk_bf16_f32 v151, v161, v211
	v_cvt_pk_bf16_f32 v152, v155, v213
	v_cvt_pk_bf16_f32 v153, v157, v217
	ds_read_b128 v[154:157], v0 offset:16384
	ds_read_b128 v[158:161], v0 offset:17408
	ds_read_b128 v[162:165], v0 offset:18432
	ds_read_b128 v[166:169], v0 offset:19456
	ds_read_b128 v[202:205], v0 offset:20480
	ds_read_b128 v[206:209], v0 offset:21504
	ds_read_b128 v[210:213], v0 offset:22528
	ds_read_b128 v[216:219], v0 offset:23552
	v_mfma_f32_16x16x32_bf16 v[90:93], v[134:137], v[146:149], v[90:93]
	v_mfma_f32_16x16x32_bf16 v[70:73], v[134:137], v[142:145], v[70:73]
	v_mfma_f32_16x16x32_bf16 v[102:105], v[126:129], v[146:149], v[102:105]
	v_mfma_f32_16x16x32_bf16 v[66:69], v[126:129], v[142:145], v[66:69]
	v_mfma_f32_16x16x32_bf16 v[98:101], v[118:121], v[146:149], v[98:101]
	v_mfma_f32_16x16x32_bf16 v[58:61], v[118:121], v[142:145], v[58:61]
	v_mfma_f32_16x16x32_bf16 v[94:97], v[110:113], v[146:149], v[94:97]
	v_mfma_f32_16x16x32_bf16 v[54:57], v[110:113], v[142:145], v[54:57]
	s_waitcnt lgkmcnt(7)
	v_mfma_f32_16x16x32_bf16 v[86:89], v[154:157], v[146:149], v[86:89]
	v_mfma_f32_16x16x32_bf16 v[46:49], v[154:157], v[142:145], v[46:49]
	s_waitcnt lgkmcnt(5)
	v_mfma_f32_16x16x32_bf16 v[82:85], v[162:165], v[146:149], v[82:85]
	v_mfma_f32_16x16x32_bf16 v[38:41], v[162:165], v[142:145], v[38:41]
	s_waitcnt lgkmcnt(3)
	v_mfma_f32_16x16x32_bf16 v[78:81], v[202:205], v[146:149], v[78:81]
	v_mfma_f32_16x16x32_bf16 v[34:37], v[202:205], v[142:145], v[34:37]
	s_waitcnt lgkmcnt(1)
	v_mfma_f32_16x16x32_bf16 v[74:77], v[210:213], v[146:149], v[74:77]
	v_mfma_f32_16x16x32_bf16 v[26:29], v[210:213], v[142:145], v[26:29]
	v_mfma_f32_16x16x32_bf16 v[90:93], v[130:133], v[138:141], v[90:93]
	v_mfma_f32_16x16x32_bf16 v[70:73], v[130:133], v[150:153], v[70:73]
	v_mfma_f32_16x16x32_bf16 v[102:105], v[122:125], v[138:141], v[102:105]
	v_mfma_f32_16x16x32_bf16 v[66:69], v[122:125], v[150:153], v[66:69]
	v_mfma_f32_16x16x32_bf16 v[98:101], v[114:117], v[138:141], v[98:101]
	v_mfma_f32_16x16x32_bf16 v[58:61], v[114:117], v[150:153], v[58:61]
	v_mfma_f32_16x16x32_bf16 v[94:97], v[106:109], v[138:141], v[94:97]
	v_mfma_f32_16x16x32_bf16 v[54:57], v[106:109], v[150:153], v[54:57]
	v_mfma_f32_16x16x32_bf16 v[86:89], v[158:161], v[138:141], v[86:89]
	v_mfma_f32_16x16x32_bf16 v[46:49], v[158:161], v[150:153], v[46:49]
	v_mfma_f32_16x16x32_bf16 v[82:85], v[166:169], v[138:141], v[82:85]
	v_mfma_f32_16x16x32_bf16 v[38:41], v[166:169], v[150:153], v[38:41]
	v_mfma_f32_16x16x32_bf16 v[78:81], v[206:209], v[138:141], v[78:81]
	v_mfma_f32_16x16x32_bf16 v[34:37], v[206:209], v[150:153], v[34:37]
	s_waitcnt lgkmcnt(0)
	v_mfma_f32_16x16x32_bf16 v[74:77], v[216:219], v[138:141], v[74:77]
	v_mfma_f32_16x16x32_bf16 v[26:29], v[216:219], v[150:153], v[26:29]
	s_xor_b32 s53, s53, 1
	s_add_i32 s49, s49, 64
	s_add_i32 s54, s54, 1
	s_add_u32 s98, s98, 0x4000
	s_addc_u32 s99, s99, 0
	s_add_u32 s2, s2, 0x2000
	s_addc_u32 s3, s3, 0
	s_cmp_lg_u32 s1, s54
	s_cbranch_scc0 .LBB0_42
	v_mov_b32_e32 v200, v199
	v_mov_b32_e32 v198, v201
	s_branch .LBB0_46

.LBB0_400:
	s_andn2_b64 vcc, exec, s[12:13]
	s_cbranch_vccz .LBB0_402
	s_ashr_i32 s1, s0, 31
	s_lshl_b64 s[12:13], s[0:1], 13
	s_add_u32 s14, s44, s12
	s_addc_u32 s15, s45, s13
	s_add_u32 s12, s47, s12
	s_addc_u32 s13, s48, s13
	global_load_dwordx4 v[98:101], v162, s[14:15]
	global_load_dwordx4 v[102:105], v164, s[14:15]
	global_load_dwordx4 v[106:109], v162, s[12:13]
	global_load_dwordx4 v[110:113], v164, s[12:13]
	s_mov_b32 s1, s0

.LBB0_412:
	s_lshl_b32 s15, s14, 14
	s_cmp_ge_u32 s94, s80
	s_cselect_b64 s[44:45], -1, 0
	v_add_u32_e32 v0, s15, v238
	s_and_b64 vcc, exec, s[44:45]
	s_waitcnt vmcnt(3)
	ds_write_b128 v0, v[146:149]
	s_waitcnt vmcnt(2)
	ds_write_b128 v0, v[150:153] offset:4096
	s_waitcnt vmcnt(1)
	ds_write_b128 v0, v[154:157] offset:8192
	s_waitcnt vmcnt(0)
	ds_write_b128 v0, v[158:161] offset:12288
	s_waitcnt lgkmcnt(0)
	s_barrier
	s_cbranch_vccnz .LBB0_414
	s_add_u32 vcc_lo, s0, 0x13957000
	s_addc_u32 vcc_hi, s1, 0
	global_load_dwordx4 v[146:149], v204, vcc
	global_load_dwordx4 v[150:153], v206, vcc
	s_add_u32 vcc_lo, s0, 0x14957000
	s_addc_u32 vcc_hi, s1, 0
	global_load_dwordx4 v[154:157], v204, vcc
	global_load_dwordx4 v[158:161], v206, vcc
